# residual-update epilogue: row sum-of-squares butterfly via v_permlane16_swap/v_permlane32_swap instead of 32 ds_bpermute round trips
# baseline (speedup 1.0000x reference)
; DI unsigned cvtpk(float lo, float hi) { f32x2_t v = {lo, hi}; bf16x2_t b = __builtin_convertvector(v, bf16x2_t); return __builtin_bit_cast(unsigned, b); }
; DI float bflo(unsigned u) { return __uint_as_float(u << 16); }
; DI float bfhi(unsigned u) { return __uint_as_float(u & 0xffff0000u); }
;     DI void operator()(const f32x4 (&acc)[2][2][4][2], const Unit& u, int wr, int wc, int fr, int fq) const {
;     ...
;                     const int row = row0 + ai * HALF + m * 16; float ss = 0.f;
; #pragma unroll
;                     for (int bj = 0; bj < 2; ++bj) {
;                         const size_t off = (size_t)row * DM + col0 + bj * HALF; const u32x4 w = bw[ai][m][bj];
;                         const f32x4 b0 = (f32x4){bflo(w.x), bfhi(w.x), bflo(w.y), bfhi(w.y)}, b1 = (f32x4){bflo(w.z), bfhi(w.z), bflo(w.w), bfhi(w.w)};
;                         const f32x4 x0 = b0 + alpha * acc[ai][bj][m][0], x1 = b1 + alpha * acc[ai][bj][m][1];
;                         if (out) { *(f32x4*)(out + off) = x0; *(f32x4*)(out + off + 4) = x1; }
;                         if (xb) { u32x4 o; o.x = cvtpk(x0[0], x0[1]); o.y = cvtpk(x0[2], x0[3]); o.z = cvtpk(x1[0], x1[1]); o.w = cvtpk(x1[2], x1[3]); *(u32x4*)(xb + off) = o; }
;                         ss += (x0[0] * x0[0] + x0[1] * x0[1]) + (x0[2] * x0[2] + x0[3] * x0[3]) + (x1[0] * x1[0] + x1[1] * x1[1]) + (x1[2] * x1[2] + x1[3] * x1[3]);
;                     }
;                     if (rss) { ss += __shfl_xor(ss, 16); ss += __shfl_xor(ss, 32); if (fq == 0) rss[(size_t)row * 16 + u.pn * 4 + wc] = ss; }
.LBB0_465:
	s_lshl_b32 s82, s95, 2
	s_nop 0
	v_cndmask_b32_e64 v202, 0, 1, s[52:53]
	v_cmp_ne_u32_e64 s[12:13], 1, v202
	s_andn2_b64 vcc, exec, s[52:53]
	s_ashr_i32 s83, s82, 31
	s_cbranch_vccnz .LBB0_469
	v_mul_f32_e32 v195, v195, v195
	v_fmac_f32_e32 v195, v194, v194
	v_mul_f32_e32 v194, v197, v197
	v_fmac_f32_e32 v194, v196, v196
	v_mul_f32_e32 v191, v191, v191
	v_add_f32_e32 v194, v195, v194
	v_fmac_f32_e32 v191, v190, v190
	v_mul_f32_e32 v187, v187, v187
	v_add_f32_e32 v190, v191, v194
	v_mul_f32_e32 v191, v193, v193
	v_fmac_f32_e32 v187, v186, v186
	v_mul_f32_e32 v186, v189, v189
	v_fmac_f32_e32 v191, v192, v192
	v_mul_f32_e32 v192, v199, v199
	v_fmac_f32_e32 v186, v188, v188
	v_and_b32_e32 v188, 64, v245
	v_add_f32_e32 v190, v191, v190
	v_mul_f32_e32 v191, v201, v201
	v_fmac_f32_e32 v192, v198, v198
	v_add_f32_e32 v186, v187, v186
	v_xor_b32_e32 v187, 16, v245
	v_add_u32_e32 v188, 64, v188
	v_fmac_f32_e32 v191, v200, v200
	v_add_f32_e32 v186, v192, v186
	v_cmp_lt_i32_e32 vcc, v187, v188
	v_add_f32_e32 v186, v191, v186
	v_add_f32_e32 v186, v190, v186
	v_cndmask_b32_e32 v187, v245, v187, vcc
	v_lshlrev_b32_e32 v187, 2, v187
	v_mov_b32_e32 v187, v186
	s_nop 1
	v_permlane16_swap_b32_e32 v187, v186
	s_waitcnt lgkmcnt(0)
	v_add_f32_e32 v186, v186, v187
	v_xor_b32_e32 v187, 32, v245
	v_cmp_lt_i32_e32 vcc, v187, v188
	s_nop 1
	v_cndmask_b32_e32 v187, v245, v187, vcc
	v_lshlrev_b32_e32 v187, 2, v187
	v_mov_b32_e32 v187, v186
	s_nop 1
	v_permlane32_swap_b32_e32 v187, v186
	s_and_saveexec_b64 vcc, s[4:5]
	s_cbranch_execz .LBB0_468
	v_readlane_b32 s26, v255, 5
	s_waitcnt lgkmcnt(0)
	v_add_f32_e32 v188, v186, v187
	v_lshlrev_b64 v[186:187], 6, v[234:235]
	v_readlane_b32 s27, v255, 6
	s_lshl_b32 s46, s43, 2
	s_nop 0
	v_lshl_add_u64 v[186:187], s[26:27], 0, v[186:187]
	v_lshl_add_u64 v[186:187], s[82:83], 2, v[186:187]
	v_lshl_add_u64 v[186:187], v[186:187], 0, s[46:47]
	global_store_dword v[186:187], v188, off

; DI unsigned cvtpk(float lo, float hi) { f32x2_t v = {lo, hi}; bf16x2_t b = __builtin_convertvector(v, bf16x2_t); return __builtin_bit_cast(unsigned, b); }
; DI float bflo(unsigned u) { return __uint_as_float(u << 16); }
; DI float bfhi(unsigned u) { return __uint_as_float(u & 0xffff0000u); }
;     DI void operator()(const f32x4 (&acc)[2][2][4][2], const Unit& u, int wr, int wc, int fr, int fq) const {
;     ...
;                     const int row = row0 + ai * HALF + m * 16; float ss = 0.f;
; #pragma unroll
;                     for (int bj = 0; bj < 2; ++bj) {
;                         const size_t off = (size_t)row * DM + col0 + bj * HALF; const u32x4 w = bw[ai][m][bj];
;                         const f32x4 b0 = (f32x4){bflo(w.x), bfhi(w.x), bflo(w.y), bfhi(w.y)}, b1 = (f32x4){bflo(w.z), bfhi(w.z), bflo(w.w), bfhi(w.w)};
;                         const f32x4 x0 = b0 + alpha * acc[ai][bj][m][0], x1 = b1 + alpha * acc[ai][bj][m][1];
;                         if (out) { *(f32x4*)(out + off) = x0; *(f32x4*)(out + off + 4) = x1; }
;                         if (xb) { u32x4 o; o.x = cvtpk(x0[0], x0[1]); o.y = cvtpk(x0[2], x0[3]); o.z = cvtpk(x1[0], x1[1]); o.w = cvtpk(x1[2], x1[3]); *(u32x4*)(xb + off) = o; }
;                         ss += (x0[0] * x0[0] + x0[1] * x0[1]) + (x0[2] * x0[2] + x0[3] * x0[3]) + (x1[0] * x1[0] + x1[1] * x1[1]) + (x1[2] * x1[2] + x1[3] * x1[3]);
;                     }
;                     if (rss) { ss += __shfl_xor(ss, 16); ss += __shfl_xor(ss, 32); if (fq == 0) rss[(size_t)row * 16 + u.pn * 4 + wc] = ss; }
.LBB0_477:
	s_and_b64 vcc, exec, s[12:13]
	s_cbranch_vccnz .LBB0_481
	v_mul_f32_e32 v183, v183, v183
	v_fmac_f32_e32 v183, v182, v182
	v_mul_f32_e32 v182, v185, v185
	v_fmac_f32_e32 v182, v184, v184
	v_add_f32_e32 v182, v183, v182
	v_mul_f32_e32 v183, v187, v187
	v_fmac_f32_e32 v183, v186, v186
	v_mul_f32_e32 v179, v179, v179
	v_add_f32_e32 v182, v183, v182
	v_mul_f32_e32 v183, v189, v189
	v_fmac_f32_e32 v179, v178, v178
	v_mul_f32_e32 v178, v181, v181
	v_fmac_f32_e32 v183, v188, v188
	v_mul_f32_e32 v184, v191, v191
	v_fmac_f32_e32 v178, v180, v180
	v_and_b32_e32 v180, 64, v245
	v_add_f32_e32 v182, v183, v182
	v_mul_f32_e32 v183, v193, v193
	v_fmac_f32_e32 v184, v190, v190
	v_add_f32_e32 v178, v179, v178
	v_xor_b32_e32 v179, 16, v245
	v_add_u32_e32 v180, 64, v180
	v_fmac_f32_e32 v183, v192, v192
	v_add_f32_e32 v178, v184, v178
	v_cmp_lt_i32_e32 vcc, v179, v180
	v_add_f32_e32 v178, v183, v178
	v_add_f32_e32 v178, v182, v178
	v_cndmask_b32_e32 v179, v245, v179, vcc
	v_lshlrev_b32_e32 v179, 2, v179
	v_mov_b32_e32 v179, v178
	s_nop 1
	v_permlane16_swap_b32_e32 v179, v178
	s_waitcnt lgkmcnt(0)
	v_add_f32_e32 v178, v178, v179
	v_xor_b32_e32 v179, 32, v245
	v_cmp_lt_i32_e32 vcc, v179, v180
	s_nop 1
	v_cndmask_b32_e32 v179, v245, v179, vcc
	v_lshlrev_b32_e32 v179, 2, v179
	v_mov_b32_e32 v179, v178
	s_nop 1
	v_permlane32_swap_b32_e32 v179, v178
	s_and_saveexec_b64 vcc, s[4:5]
	s_cbranch_execz .LBB0_480
	v_readlane_b32 s26, v255, 5
	s_waitcnt lgkmcnt(0)
	v_add_f32_e32 v180, v178, v179
	v_lshlrev_b64 v[178:179], 6, v[232:233]
	v_readlane_b32 s27, v255, 6
	s_lshl_b32 s46, s43, 2
	s_nop 0
	v_lshl_add_u64 v[178:179], s[26:27], 0, v[178:179]
	v_lshl_add_u64 v[178:179], s[82:83], 2, v[178:179]
	v_lshl_add_u64 v[178:179], v[178:179], 0, s[46:47]
	global_store_dword v[178:179], v180, off

; DI unsigned cvtpk(float lo, float hi) { f32x2_t v = {lo, hi}; bf16x2_t b = __builtin_convertvector(v, bf16x2_t); return __builtin_bit_cast(unsigned, b); }
; DI float bflo(unsigned u) { return __uint_as_float(u << 16); }
; DI float bfhi(unsigned u) { return __uint_as_float(u & 0xffff0000u); }
;     DI void operator()(const f32x4 (&acc)[2][2][4][2], const Unit& u, int wr, int wc, int fr, int fq) const {
;     ...
;                     const int row = row0 + ai * HALF + m * 16; float ss = 0.f;
; #pragma unroll
;                     for (int bj = 0; bj < 2; ++bj) {
;                         const size_t off = (size_t)row * DM + col0 + bj * HALF; const u32x4 w = bw[ai][m][bj];
;                         const f32x4 b0 = (f32x4){bflo(w.x), bfhi(w.x), bflo(w.y), bfhi(w.y)}, b1 = (f32x4){bflo(w.z), bfhi(w.z), bflo(w.w), bfhi(w.w)};
;                         const f32x4 x0 = b0 + alpha * acc[ai][bj][m][0], x1 = b1 + alpha * acc[ai][bj][m][1];
;                         if (out) { *(f32x4*)(out + off) = x0; *(f32x4*)(out + off + 4) = x1; }
;                         if (xb) { u32x4 o; o.x = cvtpk(x0[0], x0[1]); o.y = cvtpk(x0[2], x0[3]); o.z = cvtpk(x1[0], x1[1]); o.w = cvtpk(x1[2], x1[3]); *(u32x4*)(xb + off) = o; }
;                         ss += (x0[0] * x0[0] + x0[1] * x0[1]) + (x0[2] * x0[2] + x0[3] * x0[3]) + (x1[0] * x1[0] + x1[1] * x1[1]) + (x1[2] * x1[2] + x1[3] * x1[3]);
;                     }
;                     if (rss) { ss += __shfl_xor(ss, 16); ss += __shfl_xor(ss, 32); if (fq == 0) rss[(size_t)row * 16 + u.pn * 4 + wc] = ss; }
.LBB0_489:
	s_and_b64 vcc, exec, s[12:13]
	s_cbranch_vccnz .LBB0_493
	v_mul_f32_e32 v175, v175, v175
	v_fmac_f32_e32 v175, v174, v174
	v_mul_f32_e32 v174, v177, v177
	v_fmac_f32_e32 v174, v176, v176
	v_add_f32_e32 v174, v175, v174
	v_mul_f32_e32 v175, v179, v179
	v_fmac_f32_e32 v175, v178, v178
	v_mul_f32_e32 v171, v171, v171
	v_add_f32_e32 v174, v175, v174
	v_mul_f32_e32 v175, v181, v181
	v_fmac_f32_e32 v171, v170, v170
	v_mul_f32_e32 v170, v173, v173
	v_fmac_f32_e32 v175, v180, v180
	v_mul_f32_e32 v176, v183, v183
	v_fmac_f32_e32 v170, v172, v172
	v_and_b32_e32 v172, 64, v245
	v_add_f32_e32 v174, v175, v174
	v_mul_f32_e32 v175, v185, v185
	v_fmac_f32_e32 v176, v182, v182
	v_add_f32_e32 v170, v171, v170
	v_xor_b32_e32 v171, 16, v245
	v_add_u32_e32 v172, 64, v172
	v_fmac_f32_e32 v175, v184, v184
	v_add_f32_e32 v170, v176, v170
	v_cmp_lt_i32_e32 vcc, v171, v172
	v_add_f32_e32 v170, v175, v170
	v_add_f32_e32 v170, v174, v170
	v_cndmask_b32_e32 v171, v245, v171, vcc
	v_lshlrev_b32_e32 v171, 2, v171
	v_mov_b32_e32 v171, v170
	s_nop 1
	v_permlane16_swap_b32_e32 v171, v170
	s_waitcnt lgkmcnt(0)
	v_add_f32_e32 v170, v170, v171
	v_xor_b32_e32 v171, 32, v245
	v_cmp_lt_i32_e32 vcc, v171, v172
	s_nop 1
	v_cndmask_b32_e32 v171, v245, v171, vcc
	v_lshlrev_b32_e32 v171, 2, v171
	v_mov_b32_e32 v171, v170
	s_nop 1
	v_permlane32_swap_b32_e32 v171, v170
	s_and_saveexec_b64 vcc, s[4:5]
	s_cbranch_execz .LBB0_492
	v_readlane_b32 s26, v255, 5
	s_waitcnt lgkmcnt(0)
	v_add_f32_e32 v172, v170, v171
	v_lshlrev_b64 v[170:171], 6, v[230:231]
	v_readlane_b32 s27, v255, 6
	s_lshl_b32 s46, s43, 2
	s_nop 0
	v_lshl_add_u64 v[170:171], s[26:27], 0, v[170:171]
	v_lshl_add_u64 v[170:171], s[82:83], 2, v[170:171]
	v_lshl_add_u64 v[170:171], v[170:171], 0, s[46:47]
	global_store_dword v[170:171], v172, off

; DI unsigned cvtpk(float lo, float hi) { f32x2_t v = {lo, hi}; bf16x2_t b = __builtin_convertvector(v, bf16x2_t); return __builtin_bit_cast(unsigned, b); }
; DI float bflo(unsigned u) { return __uint_as_float(u << 16); }
; DI float bfhi(unsigned u) { return __uint_as_float(u & 0xffff0000u); }
;     DI void operator()(const f32x4 (&acc)[2][2][4][2], const Unit& u, int wr, int wc, int fr, int fq) const {
;     ...
;                     const int row = row0 + ai * HALF + m * 16; float ss = 0.f;
; #pragma unroll
;                     for (int bj = 0; bj < 2; ++bj) {
;                         const size_t off = (size_t)row * DM + col0 + bj * HALF; const u32x4 w = bw[ai][m][bj];
;                         const f32x4 b0 = (f32x4){bflo(w.x), bfhi(w.x), bflo(w.y), bfhi(w.y)}, b1 = (f32x4){bflo(w.z), bfhi(w.z), bflo(w.w), bfhi(w.w)};
;                         const f32x4 x0 = b0 + alpha * acc[ai][bj][m][0], x1 = b1 + alpha * acc[ai][bj][m][1];
;                         if (out) { *(f32x4*)(out + off) = x0; *(f32x4*)(out + off + 4) = x1; }
;                         if (xb) { u32x4 o; o.x = cvtpk(x0[0], x0[1]); o.y = cvtpk(x0[2], x0[3]); o.z = cvtpk(x1[0], x1[1]); o.w = cvtpk(x1[2], x1[3]); *(u32x4*)(xb + off) = o; }
;                         ss += (x0[0] * x0[0] + x0[1] * x0[1]) + (x0[2] * x0[2] + x0[3] * x0[3]) + (x1[0] * x1[0] + x1[1] * x1[1]) + (x1[2] * x1[2] + x1[3] * x1[3]);
;                     }
;                     if (rss) { ss += __shfl_xor(ss, 16); ss += __shfl_xor(ss, 32); if (fq == 0) rss[(size_t)row * 16 + u.pn * 4 + wc] = ss; }
.LBB0_501:
	s_and_b64 vcc, exec, s[12:13]
	s_cbranch_vccnz .LBB0_505
	v_mul_f32_e32 v167, v167, v167
	v_fmac_f32_e32 v167, v166, v166
	v_mul_f32_e32 v166, v169, v169
	v_fmac_f32_e32 v166, v168, v168
	v_add_f32_e32 v166, v167, v166
	v_mul_f32_e32 v167, v171, v171
	v_fmac_f32_e32 v167, v170, v170
	v_mul_f32_e32 v163, v163, v163
	v_add_f32_e32 v166, v167, v166
	v_mul_f32_e32 v167, v173, v173
	v_fmac_f32_e32 v163, v162, v162
	v_mul_f32_e32 v162, v165, v165
	v_fmac_f32_e32 v167, v172, v172
	v_mul_f32_e32 v168, v175, v175
	v_fmac_f32_e32 v162, v164, v164
	v_and_b32_e32 v164, 64, v245
	v_add_f32_e32 v166, v167, v166
	v_mul_f32_e32 v167, v177, v177
	v_fmac_f32_e32 v168, v174, v174
	v_add_f32_e32 v162, v163, v162
	v_xor_b32_e32 v163, 16, v245
	v_add_u32_e32 v164, 64, v164
	v_fmac_f32_e32 v167, v176, v176
	v_add_f32_e32 v162, v168, v162
	v_cmp_lt_i32_e32 vcc, v163, v164
	v_add_f32_e32 v162, v167, v162
	v_add_f32_e32 v162, v166, v162
	v_cndmask_b32_e32 v163, v245, v163, vcc
	v_lshlrev_b32_e32 v163, 2, v163
	v_mov_b32_e32 v163, v162
	s_nop 1
	v_permlane16_swap_b32_e32 v163, v162
	s_waitcnt lgkmcnt(0)
	v_add_f32_e32 v162, v162, v163
	v_xor_b32_e32 v163, 32, v245
	v_cmp_lt_i32_e32 vcc, v163, v164
	s_nop 1
	v_cndmask_b32_e32 v163, v245, v163, vcc
	v_lshlrev_b32_e32 v163, 2, v163
	v_mov_b32_e32 v163, v162
	s_nop 1
	v_permlane32_swap_b32_e32 v163, v162
	s_and_saveexec_b64 vcc, s[4:5]
	s_cbranch_execz .LBB0_504
	v_readlane_b32 s26, v255, 5
	s_waitcnt lgkmcnt(0)
	v_add_f32_e32 v164, v162, v163
	v_lshlrev_b64 v[162:163], 6, v[228:229]
	v_readlane_b32 s27, v255, 6
	s_lshl_b32 s46, s43, 2
	s_nop 0
	v_lshl_add_u64 v[162:163], s[26:27], 0, v[162:163]
	v_lshl_add_u64 v[162:163], s[82:83], 2, v[162:163]
	v_lshl_add_u64 v[162:163], v[162:163], 0, s[46:47]
	global_store_dword v[162:163], v164, off

; DI unsigned cvtpk(float lo, float hi) { f32x2_t v = {lo, hi}; bf16x2_t b = __builtin_convertvector(v, bf16x2_t); return __builtin_bit_cast(unsigned, b); }
; DI float bflo(unsigned u) { return __uint_as_float(u << 16); }
; DI float bfhi(unsigned u) { return __uint_as_float(u & 0xffff0000u); }
;     DI void operator()(const f32x4 (&acc)[2][2][4][2], const Unit& u, int wr, int wc, int fr, int fq) const {
;     ...
;                     const int row = row0 + ai * HALF + m * 16; float ss = 0.f;
; #pragma unroll
;                     for (int bj = 0; bj < 2; ++bj) {
;                         const size_t off = (size_t)row * DM + col0 + bj * HALF; const u32x4 w = bw[ai][m][bj];
;                         const f32x4 b0 = (f32x4){bflo(w.x), bfhi(w.x), bflo(w.y), bfhi(w.y)}, b1 = (f32x4){bflo(w.z), bfhi(w.z), bflo(w.w), bfhi(w.w)};
;                         const f32x4 x0 = b0 + alpha * acc[ai][bj][m][0], x1 = b1 + alpha * acc[ai][bj][m][1];
;                         if (out) { *(f32x4*)(out + off) = x0; *(f32x4*)(out + off + 4) = x1; }
;                         if (xb) { u32x4 o; o.x = cvtpk(x0[0], x0[1]); o.y = cvtpk(x0[2], x0[3]); o.z = cvtpk(x1[0], x1[1]); o.w = cvtpk(x1[2], x1[3]); *(u32x4*)(xb + off) = o; }
;                         ss += (x0[0] * x0[0] + x0[1] * x0[1]) + (x0[2] * x0[2] + x0[3] * x0[3]) + (x1[0] * x1[0] + x1[1] * x1[1]) + (x1[2] * x1[2] + x1[3] * x1[3]);
;                     }
;                     if (rss) { ss += __shfl_xor(ss, 16); ss += __shfl_xor(ss, 32); if (fq == 0) rss[(size_t)row * 16 + u.pn * 4 + wc] = ss; }
.LBB0_513:
	s_and_b64 vcc, exec, s[12:13]
	s_cbranch_vccnz .LBB0_517
	v_mul_f32_e32 v159, v159, v159
	v_fmac_f32_e32 v159, v158, v158
	v_mul_f32_e32 v158, v161, v161
	v_fmac_f32_e32 v158, v160, v160
	v_add_f32_e32 v158, v159, v158
	v_mul_f32_e32 v159, v163, v163
	v_fmac_f32_e32 v159, v162, v162
	v_mul_f32_e32 v155, v155, v155
	v_add_f32_e32 v158, v159, v158
	v_mul_f32_e32 v159, v165, v165
	v_fmac_f32_e32 v155, v154, v154
	v_mul_f32_e32 v154, v157, v157
	v_fmac_f32_e32 v159, v164, v164
	v_mul_f32_e32 v160, v167, v167
	v_fmac_f32_e32 v154, v156, v156
	v_and_b32_e32 v156, 64, v245
	v_add_f32_e32 v158, v159, v158
	v_mul_f32_e32 v159, v169, v169
	v_fmac_f32_e32 v160, v166, v166
	v_add_f32_e32 v154, v155, v154
	v_xor_b32_e32 v155, 16, v245
	v_add_u32_e32 v156, 64, v156
	v_fmac_f32_e32 v159, v168, v168
	v_add_f32_e32 v154, v160, v154
	v_cmp_lt_i32_e32 vcc, v155, v156
	v_add_f32_e32 v154, v159, v154
	v_add_f32_e32 v154, v158, v154
	v_cndmask_b32_e32 v155, v245, v155, vcc
	v_lshlrev_b32_e32 v155, 2, v155
	v_mov_b32_e32 v155, v154
	s_nop 1
	v_permlane16_swap_b32_e32 v155, v154
	s_waitcnt lgkmcnt(0)
	v_add_f32_e32 v154, v154, v155
	v_xor_b32_e32 v155, 32, v245
	v_cmp_lt_i32_e32 vcc, v155, v156
	s_nop 1
	v_cndmask_b32_e32 v155, v245, v155, vcc
	v_lshlrev_b32_e32 v155, 2, v155
	v_mov_b32_e32 v155, v154
	s_nop 1
	v_permlane32_swap_b32_e32 v155, v154
	s_and_saveexec_b64 vcc, s[4:5]
	s_cbranch_execz .LBB0_516
	v_readlane_b32 s26, v255, 5
	s_waitcnt lgkmcnt(0)
	v_add_f32_e32 v156, v154, v155
	v_lshlrev_b64 v[154:155], 6, v[226:227]
	v_readlane_b32 s27, v255, 6
	s_lshl_b32 s46, s43, 2
	s_nop 0
	v_lshl_add_u64 v[154:155], s[26:27], 0, v[154:155]
	v_lshl_add_u64 v[154:155], s[82:83], 2, v[154:155]
	v_lshl_add_u64 v[154:155], v[154:155], 0, s[46:47]
	global_store_dword v[154:155], v156, off

; DI unsigned cvtpk(float lo, float hi) { f32x2_t v = {lo, hi}; bf16x2_t b = __builtin_convertvector(v, bf16x2_t); return __builtin_bit_cast(unsigned, b); }
; DI float bflo(unsigned u) { return __uint_as_float(u << 16); }
; DI float bfhi(unsigned u) { return __uint_as_float(u & 0xffff0000u); }
;     DI void operator()(const f32x4 (&acc)[2][2][4][2], const Unit& u, int wr, int wc, int fr, int fq) const {
;     ...
;                     const int row = row0 + ai * HALF + m * 16; float ss = 0.f;
; #pragma unroll
;                     for (int bj = 0; bj < 2; ++bj) {
;                         const size_t off = (size_t)row * DM + col0 + bj * HALF; const u32x4 w = bw[ai][m][bj];
;                         const f32x4 b0 = (f32x4){bflo(w.x), bfhi(w.x), bflo(w.y), bfhi(w.y)}, b1 = (f32x4){bflo(w.z), bfhi(w.z), bflo(w.w), bfhi(w.w)};
;                         const f32x4 x0 = b0 + alpha * acc[ai][bj][m][0], x1 = b1 + alpha * acc[ai][bj][m][1];
;                         if (out) { *(f32x4*)(out + off) = x0; *(f32x4*)(out + off + 4) = x1; }
;                         if (xb) { u32x4 o; o.x = cvtpk(x0[0], x0[1]); o.y = cvtpk(x0[2], x0[3]); o.z = cvtpk(x1[0], x1[1]); o.w = cvtpk(x1[2], x1[3]); *(u32x4*)(xb + off) = o; }
;                         ss += (x0[0] * x0[0] + x0[1] * x0[1]) + (x0[2] * x0[2] + x0[3] * x0[3]) + (x1[0] * x1[0] + x1[1] * x1[1]) + (x1[2] * x1[2] + x1[3] * x1[3]);
;                     }
;                     if (rss) { ss += __shfl_xor(ss, 16); ss += __shfl_xor(ss, 32); if (fq == 0) rss[(size_t)row * 16 + u.pn * 4 + wc] = ss; }
.LBB0_525:
	s_and_b64 vcc, exec, s[12:13]
	s_cbranch_vccnz .LBB0_529
	v_mul_f32_e32 v151, v151, v151
	v_fmac_f32_e32 v151, v150, v150
	v_mul_f32_e32 v150, v153, v153
	v_fmac_f32_e32 v150, v152, v152
	v_add_f32_e32 v150, v151, v150
	v_mul_f32_e32 v151, v155, v155
	v_fmac_f32_e32 v151, v154, v154
	v_mul_f32_e32 v147, v147, v147
	v_add_f32_e32 v150, v151, v150
	v_mul_f32_e32 v151, v157, v157
	v_fmac_f32_e32 v147, v146, v146
	v_mul_f32_e32 v146, v149, v149
	v_fmac_f32_e32 v151, v156, v156
	v_mul_f32_e32 v152, v159, v159
	v_fmac_f32_e32 v146, v148, v148
	v_and_b32_e32 v148, 64, v245
	v_add_f32_e32 v150, v151, v150
	v_mul_f32_e32 v151, v161, v161
	v_fmac_f32_e32 v152, v158, v158
	v_add_f32_e32 v146, v147, v146
	v_xor_b32_e32 v147, 16, v245
	v_add_u32_e32 v148, 64, v148
	v_fmac_f32_e32 v151, v160, v160
	v_add_f32_e32 v146, v152, v146
	v_cmp_lt_i32_e32 vcc, v147, v148
	v_add_f32_e32 v146, v151, v146
	v_add_f32_e32 v146, v150, v146
	v_cndmask_b32_e32 v147, v245, v147, vcc
	v_lshlrev_b32_e32 v147, 2, v147
	v_mov_b32_e32 v147, v146
	s_nop 1
	v_permlane16_swap_b32_e32 v147, v146
	s_waitcnt lgkmcnt(0)
	v_add_f32_e32 v146, v146, v147
	v_xor_b32_e32 v147, 32, v245
	v_cmp_lt_i32_e32 vcc, v147, v148
	s_nop 1
	v_cndmask_b32_e32 v147, v245, v147, vcc
	v_lshlrev_b32_e32 v147, 2, v147
	v_mov_b32_e32 v147, v146
	s_nop 1
	v_permlane32_swap_b32_e32 v147, v146
	s_and_saveexec_b64 vcc, s[4:5]
	s_cbranch_execz .LBB0_528
	v_readlane_b32 s26, v255, 5
	s_waitcnt lgkmcnt(0)
	v_add_f32_e32 v148, v146, v147
	v_lshlrev_b64 v[146:147], 6, v[224:225]
	v_readlane_b32 s27, v255, 6
	s_lshl_b32 s46, s43, 2
	s_nop 0
	v_lshl_add_u64 v[146:147], s[26:27], 0, v[146:147]
	v_lshl_add_u64 v[146:147], s[82:83], 2, v[146:147]
	v_lshl_add_u64 v[146:147], v[146:147], 0, s[46:47]
	global_store_dword v[146:147], v148, off

; DI unsigned cvtpk(float lo, float hi) { f32x2_t v = {lo, hi}; bf16x2_t b = __builtin_convertvector(v, bf16x2_t); return __builtin_bit_cast(unsigned, b); }
; DI float bflo(unsigned u) { return __uint_as_float(u << 16); }
; DI float bfhi(unsigned u) { return __uint_as_float(u & 0xffff0000u); }
;     DI void operator()(const f32x4 (&acc)[2][2][4][2], const Unit& u, int wr, int wc, int fr, int fq) const {
;     ...
;                     const int row = row0 + ai * HALF + m * 16; float ss = 0.f;
; #pragma unroll
;                     for (int bj = 0; bj < 2; ++bj) {
;                         const size_t off = (size_t)row * DM + col0 + bj * HALF; const u32x4 w = bw[ai][m][bj];
;                         const f32x4 b0 = (f32x4){bflo(w.x), bfhi(w.x), bflo(w.y), bfhi(w.y)}, b1 = (f32x4){bflo(w.z), bfhi(w.z), bflo(w.w), bfhi(w.w)};
;                         const f32x4 x0 = b0 + alpha * acc[ai][bj][m][0], x1 = b1 + alpha * acc[ai][bj][m][1];
;                         if (out) { *(f32x4*)(out + off) = x0; *(f32x4*)(out + off + 4) = x1; }
;                         if (xb) { u32x4 o; o.x = cvtpk(x0[0], x0[1]); o.y = cvtpk(x0[2], x0[3]); o.z = cvtpk(x1[0], x1[1]); o.w = cvtpk(x1[2], x1[3]); *(u32x4*)(xb + off) = o; }
;                         ss += (x0[0] * x0[0] + x0[1] * x0[1]) + (x0[2] * x0[2] + x0[3] * x0[3]) + (x1[0] * x1[0] + x1[1] * x1[1]) + (x1[2] * x1[2] + x1[3] * x1[3]);
;                     }
;                     if (rss) { ss += __shfl_xor(ss, 16); ss += __shfl_xor(ss, 32); if (fq == 0) rss[(size_t)row * 16 + u.pn * 4 + wc] = ss; }
.LBB0_537:
	s_and_b64 vcc, exec, s[12:13]
	s_cbranch_vccnz .LBB0_541
	v_mul_f32_e32 v143, v143, v143
	v_fmac_f32_e32 v143, v142, v142
	v_mul_f32_e32 v142, v145, v145
	v_fmac_f32_e32 v142, v144, v144
	v_add_f32_e32 v142, v143, v142
	v_mul_f32_e32 v143, v147, v147
	v_fmac_f32_e32 v143, v146, v146
	v_mul_f32_e32 v139, v139, v139
	v_add_f32_e32 v142, v143, v142
	v_mul_f32_e32 v143, v149, v149
	v_fmac_f32_e32 v139, v138, v138
	v_mul_f32_e32 v138, v141, v141
	v_fmac_f32_e32 v143, v148, v148
	v_mul_f32_e32 v144, v151, v151
	v_fmac_f32_e32 v138, v140, v140
	v_and_b32_e32 v140, 64, v245
	v_add_f32_e32 v142, v143, v142
	v_mul_f32_e32 v143, v153, v153
	v_fmac_f32_e32 v144, v150, v150
	v_add_f32_e32 v138, v139, v138
	v_xor_b32_e32 v139, 16, v245
	v_add_u32_e32 v140, 64, v140
	v_fmac_f32_e32 v143, v152, v152
	v_add_f32_e32 v138, v144, v138
	v_cmp_lt_i32_e32 vcc, v139, v140
	v_add_f32_e32 v138, v143, v138
	v_add_f32_e32 v138, v142, v138
	v_cndmask_b32_e32 v139, v245, v139, vcc
	v_lshlrev_b32_e32 v139, 2, v139
	v_mov_b32_e32 v139, v138
	s_nop 1
	v_permlane16_swap_b32_e32 v139, v138
	s_waitcnt lgkmcnt(0)
	v_add_f32_e32 v138, v138, v139
	v_xor_b32_e32 v139, 32, v245
	v_cmp_lt_i32_e32 vcc, v139, v140
	s_nop 1
	v_cndmask_b32_e32 v139, v245, v139, vcc
	v_lshlrev_b32_e32 v139, 2, v139
	v_mov_b32_e32 v139, v138
	s_nop 1
	v_permlane32_swap_b32_e32 v139, v138
	s_and_saveexec_b64 vcc, s[4:5]
	s_cbranch_execz .LBB0_540
	v_readlane_b32 s26, v255, 5
	s_waitcnt lgkmcnt(0)
	v_add_f32_e32 v140, v138, v139
	v_lshlrev_b64 v[138:139], 6, v[222:223]
	v_readlane_b32 s27, v255, 6
	s_lshl_b32 s46, s43, 2
	s_nop 0
	v_lshl_add_u64 v[138:139], s[26:27], 0, v[138:139]
	v_lshl_add_u64 v[138:139], s[82:83], 2, v[138:139]
	v_lshl_add_u64 v[138:139], v[138:139], 0, s[46:47]
	global_store_dword v[138:139], v140, off

; DI unsigned cvtpk(float lo, float hi) { f32x2_t v = {lo, hi}; bf16x2_t b = __builtin_convertvector(v, bf16x2_t); return __builtin_bit_cast(unsigned, b); }
; DI float bflo(unsigned u) { return __uint_as_float(u << 16); }
; DI float bfhi(unsigned u) { return __uint_as_float(u & 0xffff0000u); }
;     DI void operator()(const f32x4 (&acc)[2][2][4][2], const Unit& u, int wr, int wc, int fr, int fq) const {
;     ...
;                     const int row = row0 + ai * HALF + m * 16; float ss = 0.f;
; #pragma unroll
;                     for (int bj = 0; bj < 2; ++bj) {
;                         const size_t off = (size_t)row * DM + col0 + bj * HALF; const u32x4 w = bw[ai][m][bj];
;                         const f32x4 b0 = (f32x4){bflo(w.x), bfhi(w.x), bflo(w.y), bfhi(w.y)}, b1 = (f32x4){bflo(w.z), bfhi(w.z), bflo(w.w), bfhi(w.w)};
;                         const f32x4 x0 = b0 + alpha * acc[ai][bj][m][0], x1 = b1 + alpha * acc[ai][bj][m][1];
;                         if (out) { *(f32x4*)(out + off) = x0; *(f32x4*)(out + off + 4) = x1; }
;                         if (xb) { u32x4 o; o.x = cvtpk(x0[0], x0[1]); o.y = cvtpk(x0[2], x0[3]); o.z = cvtpk(x1[0], x1[1]); o.w = cvtpk(x1[2], x1[3]); *(u32x4*)(xb + off) = o; }
;                         ss += (x0[0] * x0[0] + x0[1] * x0[1]) + (x0[2] * x0[2] + x0[3] * x0[3]) + (x1[0] * x1[0] + x1[1] * x1[1]) + (x1[2] * x1[2] + x1[3] * x1[3]);
;                     }
;                     if (rss) { ss += __shfl_xor(ss, 16); ss += __shfl_xor(ss, 32); if (fq == 0) rss[(size_t)row * 16 + u.pn * 4 + wc] = ss; }
.LBB0_549:
	s_and_b64 vcc, exec, s[12:13]
	s_cbranch_vccnz .LBB0_553
	v_mul_f32_e32 v135, v135, v135
	v_fmac_f32_e32 v135, v134, v134
	v_mul_f32_e32 v134, v137, v137
	v_fmac_f32_e32 v134, v136, v136
	v_add_f32_e32 v134, v135, v134
	v_mul_f32_e32 v135, v139, v139
	v_fmac_f32_e32 v135, v138, v138
	v_mul_f32_e32 v131, v131, v131
	v_add_f32_e32 v134, v135, v134
	v_mul_f32_e32 v135, v141, v141
	v_fmac_f32_e32 v131, v130, v130
	v_mul_f32_e32 v130, v133, v133
	v_fmac_f32_e32 v135, v140, v140
	v_mul_f32_e32 v136, v143, v143
	v_fmac_f32_e32 v130, v132, v132
	v_and_b32_e32 v132, 64, v245
	v_add_f32_e32 v134, v135, v134
	v_mul_f32_e32 v135, v145, v145
	v_fmac_f32_e32 v136, v142, v142
	v_add_f32_e32 v130, v131, v130
	v_xor_b32_e32 v131, 16, v245
	v_add_u32_e32 v132, 64, v132
	v_fmac_f32_e32 v135, v144, v144
	v_add_f32_e32 v130, v136, v130
	v_cmp_lt_i32_e32 vcc, v131, v132
	v_add_f32_e32 v130, v135, v130
	v_add_f32_e32 v130, v134, v130
	v_cndmask_b32_e32 v131, v245, v131, vcc
	v_lshlrev_b32_e32 v131, 2, v131
	v_mov_b32_e32 v131, v130
	s_nop 1
	v_permlane16_swap_b32_e32 v131, v130
	s_waitcnt lgkmcnt(0)
	v_add_f32_e32 v130, v130, v131
	v_xor_b32_e32 v131, 32, v245
	v_cmp_lt_i32_e32 vcc, v131, v132
	s_nop 1
	v_cndmask_b32_e32 v131, v245, v131, vcc
	v_lshlrev_b32_e32 v131, 2, v131
	v_mov_b32_e32 v131, v130
	s_nop 1
	v_permlane32_swap_b32_e32 v131, v130
	s_and_saveexec_b64 s[10:11], s[4:5]
	s_cbranch_execz .LBB0_552
	v_readlane_b32 s12, v255, 5
	s_waitcnt lgkmcnt(0)
	v_add_f32_e32 v132, v130, v131
	v_lshlrev_b64 v[130:131], 6, v[218:219]
	v_readlane_b32 s13, v255, 6
	s_lshl_b32 s46, s43, 2
	s_nop 0
	v_lshl_add_u64 v[130:131], s[12:13], 0, v[130:131]
	v_lshl_add_u64 v[130:131], s[82:83], 2, v[130:131]
	v_lshl_add_u64 v[130:131], v[130:131], 0, s[46:47]
	global_store_dword v[130:131], v132, off

; DI unsigned cvtpk(float lo, float hi) { f32x2_t v = {lo, hi}; bf16x2_t b = __builtin_convertvector(v, bf16x2_t); return __builtin_bit_cast(unsigned, b); }
;     DI void operator()(const f32x4 (&acc)[2][2][4][2], const Unit& u, int wr, int wc, int fr, int fq) const {
;     ...
;                 const int row = row0 + ai * HALF + m * 16; float ss = 0.f;
; #pragma unroll
;                 for (int bj = 0; bj < 2; ++bj) {
;                     const size_t off = (size_t)row * DM + col0 + bj * HALF;
;                     const f32x4 b0 = *(const f32x4*)(base + off), b1 = *(const f32x4*)(base + off + 4);
;                     const f32x4 x0 = b0 + alpha * acc[ai][bj][m][0], x1 = b1 + alpha * acc[ai][bj][m][1];
;                     if (out) { *(f32x4*)(out + off) = x0; *(f32x4*)(out + off + 4) = x1; }
;                     if (xb) { u32x4 w; w.x = cvtpk(x0[0], x0[1]); w.y = cvtpk(x0[2], x0[3]); w.z = cvtpk(x1[0], x1[1]); w.w = cvtpk(x1[2], x1[3]); *(u32x4*)(xb + off) = w; }
;                     ss += (x0[0] * x0[0] + x0[1] * x0[1]) + (x0[2] * x0[2] + x0[3] * x0[3]) + (x1[0] * x1[0] + x1[1] * x1[1]) + (x1[2] * x1[2] + x1[3] * x1[3]);
;                 }
;                 if (rss) { ss += __shfl_xor(ss, 16); ss += __shfl_xor(ss, 32); if (fq == 0) rss[(size_t)row * 16 + u.pn * 4 + wc] = ss; }
.LBB0_562:
	s_lshl_b32 s82, s95, 2
	v_cndmask_b32_e64 v130, 0, 1, s[52:53]
	v_cmp_ne_u32_e64 s[12:13], 1, v130
	s_andn2_b64 vcc, exec, s[52:53]
	s_ashr_i32 s83, s82, 31
	s_cbranch_vccnz .LBB0_566
	v_mul_f32_e32 v127, v127, v127
	v_mul_f32_e32 v117, v117, v117
	v_mul_f32_e32 v115, v115, v115
	v_fmac_f32_e32 v127, v126, v126
	v_mul_f32_e32 v126, v129, v129
	v_fmac_f32_e32 v117, v116, v116
	v_fmac_f32_e32 v115, v114, v114
	v_mul_f32_e32 v114, v119, v119
	v_mul_f32_e32 v116, v121, v121
	v_fmac_f32_e32 v126, v128, v128
	v_mul_f32_e32 v123, v123, v123
	v_fmac_f32_e32 v114, v118, v118
	v_fmac_f32_e32 v116, v120, v120
	v_add_f32_e32 v126, v127, v126
	v_fmac_f32_e32 v123, v122, v122
	v_add_f32_e32 v114, v114, v116
	v_and_b32_e32 v116, 64, v245
	v_add_f32_e32 v122, v123, v126
	v_mul_f32_e32 v123, v125, v125
	v_add_f32_e32 v114, v115, v114
	v_xor_b32_e32 v115, 16, v245
	v_add_u32_e32 v116, 64, v116
	v_fmac_f32_e32 v123, v124, v124
	v_cmp_lt_i32_e32 vcc, v115, v116
	v_add_f32_e32 v122, v123, v122
	v_add_f32_e32 v114, v117, v114
	v_cndmask_b32_e32 v115, v245, v115, vcc
	v_add_f32_e32 v114, v122, v114
	v_lshlrev_b32_e32 v115, 2, v115
	v_mov_b32_e32 v115, v114
	s_nop 1
	v_permlane16_swap_b32_e32 v115, v114
	s_waitcnt lgkmcnt(0)
	v_add_f32_e32 v114, v114, v115
	v_xor_b32_e32 v115, 32, v245
	v_cmp_lt_i32_e32 vcc, v115, v116
	s_nop 1
	v_cndmask_b32_e32 v115, v245, v115, vcc
	v_lshlrev_b32_e32 v115, 2, v115
	v_mov_b32_e32 v115, v114
	s_nop 1
	v_permlane32_swap_b32_e32 v115, v114
	s_and_saveexec_b64 vcc, s[4:5]
	s_cbranch_execz .LBB0_565
	v_readlane_b32 s26, v255, 5
	s_waitcnt lgkmcnt(0)
	v_add_f32_e32 v116, v114, v115
	v_lshlrev_b64 v[114:115], 6, v[234:235]
	v_readlane_b32 s27, v255, 6
	s_lshl_b32 s46, s43, 2
	s_nop 0
	v_lshl_add_u64 v[114:115], s[26:27], 0, v[114:115]
	v_lshl_add_u64 v[114:115], s[82:83], 2, v[114:115]
	v_lshl_add_u64 v[114:115], v[114:115], 0, s[46:47]
	global_store_dword v[114:115], v116, off

; DI unsigned cvtpk(float lo, float hi) { f32x2_t v = {lo, hi}; bf16x2_t b = __builtin_convertvector(v, bf16x2_t); return __builtin_bit_cast(unsigned, b); }
;     DI void operator()(const f32x4 (&acc)[2][2][4][2], const Unit& u, int wr, int wc, int fr, int fq) const {
;     ...
;                 const int row = row0 + ai * HALF + m * 16; float ss = 0.f;
; #pragma unroll
;                 for (int bj = 0; bj < 2; ++bj) {
;                     const size_t off = (size_t)row * DM + col0 + bj * HALF;
;                     const f32x4 b0 = *(const f32x4*)(base + off), b1 = *(const f32x4*)(base + off + 4);
;                     const f32x4 x0 = b0 + alpha * acc[ai][bj][m][0], x1 = b1 + alpha * acc[ai][bj][m][1];
;                     if (out) { *(f32x4*)(out + off) = x0; *(f32x4*)(out + off + 4) = x1; }
;                     if (xb) { u32x4 w; w.x = cvtpk(x0[0], x0[1]); w.y = cvtpk(x0[2], x0[3]); w.z = cvtpk(x1[0], x1[1]); w.w = cvtpk(x1[2], x1[3]); *(u32x4*)(xb + off) = w; }
;                     ss += (x0[0] * x0[0] + x0[1] * x0[1]) + (x0[2] * x0[2] + x0[3] * x0[3]) + (x1[0] * x1[0] + x1[1] * x1[1]) + (x1[2] * x1[2] + x1[3] * x1[3]);
;                 }
;                 if (rss) { ss += __shfl_xor(ss, 16); ss += __shfl_xor(ss, 32); if (fq == 0) rss[(size_t)row * 16 + u.pn * 4 + wc] = ss; }
.LBB0_574:
	s_and_b64 vcc, exec, s[12:13]
	s_cbranch_vccnz .LBB0_578
	v_mul_f32_e32 v111, v111, v111
	v_mul_f32_e32 v101, v101, v101
	v_mul_f32_e32 v99, v99, v99
	v_fmac_f32_e32 v111, v110, v110
	v_mul_f32_e32 v110, v113, v113
	v_fmac_f32_e32 v101, v100, v100
	v_fmac_f32_e32 v99, v98, v98
	v_mul_f32_e32 v98, v103, v103
	v_mul_f32_e32 v100, v105, v105
	v_fmac_f32_e32 v110, v112, v112
	v_mul_f32_e32 v107, v107, v107
	v_fmac_f32_e32 v98, v102, v102
	v_fmac_f32_e32 v100, v104, v104
	v_add_f32_e32 v110, v111, v110
	v_fmac_f32_e32 v107, v106, v106
	v_add_f32_e32 v98, v98, v100
	v_and_b32_e32 v100, 64, v245
	v_add_f32_e32 v106, v107, v110
	v_mul_f32_e32 v107, v109, v109
	v_add_f32_e32 v98, v99, v98
	v_xor_b32_e32 v99, 16, v245
	v_add_u32_e32 v100, 64, v100
	v_fmac_f32_e32 v107, v108, v108
	v_cmp_lt_i32_e32 vcc, v99, v100
	v_add_f32_e32 v106, v107, v106
	v_add_f32_e32 v98, v101, v98
	v_cndmask_b32_e32 v99, v245, v99, vcc
	v_add_f32_e32 v98, v106, v98
	v_lshlrev_b32_e32 v99, 2, v99
	v_mov_b32_e32 v99, v98
	s_nop 1
	v_permlane16_swap_b32_e32 v99, v98
	s_waitcnt lgkmcnt(0)
	v_add_f32_e32 v98, v98, v99
	v_xor_b32_e32 v99, 32, v245
	v_cmp_lt_i32_e32 vcc, v99, v100
	s_nop 1
	v_cndmask_b32_e32 v99, v245, v99, vcc
	v_lshlrev_b32_e32 v99, 2, v99
	v_mov_b32_e32 v99, v98
	s_nop 1
	v_permlane32_swap_b32_e32 v99, v98
	s_and_saveexec_b64 vcc, s[4:5]
	s_cbranch_execz .LBB0_577
	v_readlane_b32 s26, v255, 5
	s_waitcnt lgkmcnt(0)
	v_add_f32_e32 v100, v98, v99
	v_lshlrev_b64 v[98:99], 6, v[232:233]
	v_readlane_b32 s27, v255, 6
	s_lshl_b32 s46, s43, 2
	s_nop 0
	v_lshl_add_u64 v[98:99], s[26:27], 0, v[98:99]
	v_lshl_add_u64 v[98:99], s[82:83], 2, v[98:99]
	v_lshl_add_u64 v[98:99], v[98:99], 0, s[46:47]
	global_store_dword v[98:99], v100, off

; DI unsigned cvtpk(float lo, float hi) { f32x2_t v = {lo, hi}; bf16x2_t b = __builtin_convertvector(v, bf16x2_t); return __builtin_bit_cast(unsigned, b); }
;     DI void operator()(const f32x4 (&acc)[2][2][4][2], const Unit& u, int wr, int wc, int fr, int fq) const {
;     ...
;                 const int row = row0 + ai * HALF + m * 16; float ss = 0.f;
; #pragma unroll
;                 for (int bj = 0; bj < 2; ++bj) {
;                     const size_t off = (size_t)row * DM + col0 + bj * HALF;
;                     const f32x4 b0 = *(const f32x4*)(base + off), b1 = *(const f32x4*)(base + off + 4);
;                     const f32x4 x0 = b0 + alpha * acc[ai][bj][m][0], x1 = b1 + alpha * acc[ai][bj][m][1];
;                     if (out) { *(f32x4*)(out + off) = x0; *(f32x4*)(out + off + 4) = x1; }
;                     if (xb) { u32x4 w; w.x = cvtpk(x0[0], x0[1]); w.y = cvtpk(x0[2], x0[3]); w.z = cvtpk(x1[0], x1[1]); w.w = cvtpk(x1[2], x1[3]); *(u32x4*)(xb + off) = w; }
;                     ss += (x0[0] * x0[0] + x0[1] * x0[1]) + (x0[2] * x0[2] + x0[3] * x0[3]) + (x1[0] * x1[0] + x1[1] * x1[1]) + (x1[2] * x1[2] + x1[3] * x1[3]);
;                 }
;                 if (rss) { ss += __shfl_xor(ss, 16); ss += __shfl_xor(ss, 32); if (fq == 0) rss[(size_t)row * 16 + u.pn * 4 + wc] = ss; }
.LBB0_586:
	s_and_b64 vcc, exec, s[12:13]
	s_cbranch_vccnz .LBB0_590
	v_mul_f32_e32 v95, v95, v95
	v_mul_f32_e32 v85, v85, v85
	v_mul_f32_e32 v83, v83, v83
	v_fmac_f32_e32 v95, v94, v94
	v_mul_f32_e32 v94, v97, v97
	v_fmac_f32_e32 v85, v84, v84
	v_fmac_f32_e32 v83, v82, v82
	v_mul_f32_e32 v82, v87, v87
	v_mul_f32_e32 v84, v89, v89
	v_fmac_f32_e32 v94, v96, v96
	v_mul_f32_e32 v91, v91, v91
	v_fmac_f32_e32 v82, v86, v86
	v_fmac_f32_e32 v84, v88, v88
	v_add_f32_e32 v94, v95, v94
	v_fmac_f32_e32 v91, v90, v90
	v_add_f32_e32 v82, v82, v84
	v_and_b32_e32 v84, 64, v245
	v_add_f32_e32 v90, v91, v94
	v_mul_f32_e32 v91, v93, v93
	v_add_f32_e32 v82, v83, v82
	v_xor_b32_e32 v83, 16, v245
	v_add_u32_e32 v84, 64, v84
	v_fmac_f32_e32 v91, v92, v92
	v_cmp_lt_i32_e32 vcc, v83, v84
	v_add_f32_e32 v90, v91, v90
	v_add_f32_e32 v82, v85, v82
	v_cndmask_b32_e32 v83, v245, v83, vcc
	v_add_f32_e32 v82, v90, v82
	v_lshlrev_b32_e32 v83, 2, v83
	v_mov_b32_e32 v83, v82
	s_nop 1
	v_permlane16_swap_b32_e32 v83, v82
	s_waitcnt lgkmcnt(0)
	v_add_f32_e32 v82, v82, v83
	v_xor_b32_e32 v83, 32, v245
	v_cmp_lt_i32_e32 vcc, v83, v84
	s_nop 1
	v_cndmask_b32_e32 v83, v245, v83, vcc
	v_lshlrev_b32_e32 v83, 2, v83
	v_mov_b32_e32 v83, v82
	s_nop 1
	v_permlane32_swap_b32_e32 v83, v82
	s_and_saveexec_b64 vcc, s[4:5]
	s_cbranch_execz .LBB0_589
	v_readlane_b32 s26, v255, 5
	s_waitcnt lgkmcnt(0)
	v_add_f32_e32 v84, v82, v83
	v_lshlrev_b64 v[82:83], 6, v[230:231]
	v_readlane_b32 s27, v255, 6
	s_lshl_b32 s46, s43, 2
	s_nop 0
	v_lshl_add_u64 v[82:83], s[26:27], 0, v[82:83]
	v_lshl_add_u64 v[82:83], s[82:83], 2, v[82:83]
	v_lshl_add_u64 v[82:83], v[82:83], 0, s[46:47]
	global_store_dword v[82:83], v84, off

; DI unsigned cvtpk(float lo, float hi) { f32x2_t v = {lo, hi}; bf16x2_t b = __builtin_convertvector(v, bf16x2_t); return __builtin_bit_cast(unsigned, b); }
;     DI void operator()(const f32x4 (&acc)[2][2][4][2], const Unit& u, int wr, int wc, int fr, int fq) const {
;     ...
;                 const int row = row0 + ai * HALF + m * 16; float ss = 0.f;
; #pragma unroll
;                 for (int bj = 0; bj < 2; ++bj) {
;                     const size_t off = (size_t)row * DM + col0 + bj * HALF;
;                     const f32x4 b0 = *(const f32x4*)(base + off), b1 = *(const f32x4*)(base + off + 4);
;                     const f32x4 x0 = b0 + alpha * acc[ai][bj][m][0], x1 = b1 + alpha * acc[ai][bj][m][1];
;                     if (out) { *(f32x4*)(out + off) = x0; *(f32x4*)(out + off + 4) = x1; }
;                     if (xb) { u32x4 w; w.x = cvtpk(x0[0], x0[1]); w.y = cvtpk(x0[2], x0[3]); w.z = cvtpk(x1[0], x1[1]); w.w = cvtpk(x1[2], x1[3]); *(u32x4*)(xb + off) = w; }
;                     ss += (x0[0] * x0[0] + x0[1] * x0[1]) + (x0[2] * x0[2] + x0[3] * x0[3]) + (x1[0] * x1[0] + x1[1] * x1[1]) + (x1[2] * x1[2] + x1[3] * x1[3]);
;                 }
;                 if (rss) { ss += __shfl_xor(ss, 16); ss += __shfl_xor(ss, 32); if (fq == 0) rss[(size_t)row * 16 + u.pn * 4 + wc] = ss; }
.LBB0_598:
	s_and_b64 vcc, exec, s[12:13]
	s_cbranch_vccnz .LBB0_602
	v_mul_f32_e32 v79, v79, v79
	v_mul_f32_e32 v69, v69, v69
	v_mul_f32_e32 v67, v67, v67
	v_fmac_f32_e32 v79, v78, v78
	v_mul_f32_e32 v78, v81, v81
	v_fmac_f32_e32 v69, v68, v68
	v_fmac_f32_e32 v67, v66, v66
	v_mul_f32_e32 v66, v71, v71
	v_mul_f32_e32 v68, v73, v73
	v_fmac_f32_e32 v78, v80, v80
	v_mul_f32_e32 v75, v75, v75
	v_fmac_f32_e32 v66, v70, v70
	v_fmac_f32_e32 v68, v72, v72
	v_add_f32_e32 v78, v79, v78
	v_fmac_f32_e32 v75, v74, v74
	v_add_f32_e32 v66, v66, v68
	v_and_b32_e32 v68, 64, v245
	v_add_f32_e32 v74, v75, v78
	v_mul_f32_e32 v75, v77, v77
	v_add_f32_e32 v66, v67, v66
	v_xor_b32_e32 v67, 16, v245
	v_add_u32_e32 v68, 64, v68
	v_fmac_f32_e32 v75, v76, v76
	v_cmp_lt_i32_e32 vcc, v67, v68
	v_add_f32_e32 v74, v75, v74
	v_add_f32_e32 v66, v69, v66
	v_cndmask_b32_e32 v67, v245, v67, vcc
	v_add_f32_e32 v66, v74, v66
	v_lshlrev_b32_e32 v67, 2, v67
	v_mov_b32_e32 v67, v66
	s_nop 1
	v_permlane16_swap_b32_e32 v67, v66
	s_waitcnt lgkmcnt(0)
	v_add_f32_e32 v66, v66, v67
	v_xor_b32_e32 v67, 32, v245
	v_cmp_lt_i32_e32 vcc, v67, v68
	s_nop 1
	v_cndmask_b32_e32 v67, v245, v67, vcc
	v_lshlrev_b32_e32 v67, 2, v67
	v_mov_b32_e32 v67, v66
	s_nop 1
	v_permlane32_swap_b32_e32 v67, v66
	s_and_saveexec_b64 vcc, s[4:5]
	s_cbranch_execz .LBB0_601
	v_readlane_b32 s26, v255, 5
	s_waitcnt lgkmcnt(0)
	v_add_f32_e32 v68, v66, v67
	v_lshlrev_b64 v[66:67], 6, v[228:229]
	v_readlane_b32 s27, v255, 6
	s_lshl_b32 s46, s43, 2
	s_nop 0
	v_lshl_add_u64 v[66:67], s[26:27], 0, v[66:67]
	v_lshl_add_u64 v[66:67], s[82:83], 2, v[66:67]
	v_lshl_add_u64 v[66:67], v[66:67], 0, s[46:47]
	global_store_dword v[66:67], v68, off

; DI unsigned cvtpk(float lo, float hi) { f32x2_t v = {lo, hi}; bf16x2_t b = __builtin_convertvector(v, bf16x2_t); return __builtin_bit_cast(unsigned, b); }
;     DI void operator()(const f32x4 (&acc)[2][2][4][2], const Unit& u, int wr, int wc, int fr, int fq) const {
;     ...
;                 const int row = row0 + ai * HALF + m * 16; float ss = 0.f;
; #pragma unroll
;                 for (int bj = 0; bj < 2; ++bj) {
;                     const size_t off = (size_t)row * DM + col0 + bj * HALF;
;                     const f32x4 b0 = *(const f32x4*)(base + off), b1 = *(const f32x4*)(base + off + 4);
;                     const f32x4 x0 = b0 + alpha * acc[ai][bj][m][0], x1 = b1 + alpha * acc[ai][bj][m][1];
;                     if (out) { *(f32x4*)(out + off) = x0; *(f32x4*)(out + off + 4) = x1; }
;                     if (xb) { u32x4 w; w.x = cvtpk(x0[0], x0[1]); w.y = cvtpk(x0[2], x0[3]); w.z = cvtpk(x1[0], x1[1]); w.w = cvtpk(x1[2], x1[3]); *(u32x4*)(xb + off) = w; }
;                     ss += (x0[0] * x0[0] + x0[1] * x0[1]) + (x0[2] * x0[2] + x0[3] * x0[3]) + (x1[0] * x1[0] + x1[1] * x1[1]) + (x1[2] * x1[2] + x1[3] * x1[3]);
;                 }
;                 if (rss) { ss += __shfl_xor(ss, 16); ss += __shfl_xor(ss, 32); if (fq == 0) rss[(size_t)row * 16 + u.pn * 4 + wc] = ss; }
.LBB0_610:
	s_and_b64 vcc, exec, s[12:13]
	s_cbranch_vccnz .LBB0_614
	v_mul_f32_e32 v63, v63, v63
	v_mul_f32_e32 v53, v53, v53
	v_mul_f32_e32 v51, v51, v51
	v_fmac_f32_e32 v63, v62, v62
	v_mul_f32_e32 v62, v65, v65
	v_fmac_f32_e32 v53, v52, v52
	v_fmac_f32_e32 v51, v50, v50
	v_mul_f32_e32 v50, v55, v55
	v_mul_f32_e32 v52, v57, v57
	v_fmac_f32_e32 v62, v64, v64
	v_mul_f32_e32 v59, v59, v59
	v_fmac_f32_e32 v50, v54, v54
	v_fmac_f32_e32 v52, v56, v56
	v_add_f32_e32 v62, v63, v62
	v_fmac_f32_e32 v59, v58, v58
	v_add_f32_e32 v50, v50, v52
	v_and_b32_e32 v52, 64, v245
	v_add_f32_e32 v58, v59, v62
	v_mul_f32_e32 v59, v61, v61
	v_add_f32_e32 v50, v51, v50
	v_xor_b32_e32 v51, 16, v245
	v_add_u32_e32 v52, 64, v52
	v_fmac_f32_e32 v59, v60, v60
	v_cmp_lt_i32_e32 vcc, v51, v52
	v_add_f32_e32 v58, v59, v58
	v_add_f32_e32 v50, v53, v50
	v_cndmask_b32_e32 v51, v245, v51, vcc
	v_add_f32_e32 v50, v58, v50
	v_lshlrev_b32_e32 v51, 2, v51
	v_mov_b32_e32 v51, v50
	s_nop 1
	v_permlane16_swap_b32_e32 v51, v50
	s_waitcnt lgkmcnt(0)
	v_add_f32_e32 v50, v50, v51
	v_xor_b32_e32 v51, 32, v245
	v_cmp_lt_i32_e32 vcc, v51, v52
	s_nop 1
	v_cndmask_b32_e32 v51, v245, v51, vcc
	v_lshlrev_b32_e32 v51, 2, v51
	v_mov_b32_e32 v51, v50
	s_nop 1
	v_permlane32_swap_b32_e32 v51, v50
	s_and_saveexec_b64 vcc, s[4:5]
	s_cbranch_execz .LBB0_613
	v_readlane_b32 s26, v255, 5
	s_waitcnt lgkmcnt(0)
	v_add_f32_e32 v52, v50, v51
	v_lshlrev_b64 v[50:51], 6, v[226:227]
	v_readlane_b32 s27, v255, 6
	s_lshl_b32 s46, s43, 2
	s_nop 0
	v_lshl_add_u64 v[50:51], s[26:27], 0, v[50:51]
	v_lshl_add_u64 v[50:51], s[82:83], 2, v[50:51]
	v_lshl_add_u64 v[50:51], v[50:51], 0, s[46:47]
	global_store_dword v[50:51], v52, off

; DI unsigned cvtpk(float lo, float hi) { f32x2_t v = {lo, hi}; bf16x2_t b = __builtin_convertvector(v, bf16x2_t); return __builtin_bit_cast(unsigned, b); }
;     DI void operator()(const f32x4 (&acc)[2][2][4][2], const Unit& u, int wr, int wc, int fr, int fq) const {
;     ...
;                 const int row = row0 + ai * HALF + m * 16; float ss = 0.f;
; #pragma unroll
;                 for (int bj = 0; bj < 2; ++bj) {
;                     const size_t off = (size_t)row * DM + col0 + bj * HALF;
;                     const f32x4 b0 = *(const f32x4*)(base + off), b1 = *(const f32x4*)(base + off + 4);
;                     const f32x4 x0 = b0 + alpha * acc[ai][bj][m][0], x1 = b1 + alpha * acc[ai][bj][m][1];
;                     if (out) { *(f32x4*)(out + off) = x0; *(f32x4*)(out + off + 4) = x1; }
;                     if (xb) { u32x4 w; w.x = cvtpk(x0[0], x0[1]); w.y = cvtpk(x0[2], x0[3]); w.z = cvtpk(x1[0], x1[1]); w.w = cvtpk(x1[2], x1[3]); *(u32x4*)(xb + off) = w; }
;                     ss += (x0[0] * x0[0] + x0[1] * x0[1]) + (x0[2] * x0[2] + x0[3] * x0[3]) + (x1[0] * x1[0] + x1[1] * x1[1]) + (x1[2] * x1[2] + x1[3] * x1[3]);
;                 }
;                 if (rss) { ss += __shfl_xor(ss, 16); ss += __shfl_xor(ss, 32); if (fq == 0) rss[(size_t)row * 16 + u.pn * 4 + wc] = ss; }
.LBB0_622:
	s_and_b64 vcc, exec, s[12:13]
	s_cbranch_vccnz .LBB0_626
	v_mul_f32_e32 v47, v47, v47
	v_mul_f32_e32 v37, v37, v37
	v_mul_f32_e32 v35, v35, v35
	v_fmac_f32_e32 v47, v46, v46
	v_mul_f32_e32 v46, v49, v49
	v_fmac_f32_e32 v37, v36, v36
	v_fmac_f32_e32 v35, v34, v34
	v_mul_f32_e32 v34, v39, v39
	v_mul_f32_e32 v36, v41, v41
	v_fmac_f32_e32 v46, v48, v48
	v_mul_f32_e32 v43, v43, v43
	v_fmac_f32_e32 v34, v38, v38
	v_fmac_f32_e32 v36, v40, v40
	v_add_f32_e32 v46, v47, v46
	v_fmac_f32_e32 v43, v42, v42
	v_add_f32_e32 v34, v34, v36
	v_and_b32_e32 v36, 64, v245
	v_add_f32_e32 v42, v43, v46
	v_mul_f32_e32 v43, v45, v45
	v_add_f32_e32 v34, v35, v34
	v_xor_b32_e32 v35, 16, v245
	v_add_u32_e32 v36, 64, v36
	v_fmac_f32_e32 v43, v44, v44
	v_cmp_lt_i32_e32 vcc, v35, v36
	v_add_f32_e32 v42, v43, v42
	v_add_f32_e32 v34, v37, v34
	v_cndmask_b32_e32 v35, v245, v35, vcc
	v_add_f32_e32 v34, v42, v34
	v_lshlrev_b32_e32 v35, 2, v35
	v_mov_b32_e32 v35, v34
	s_nop 1
	v_permlane16_swap_b32_e32 v35, v34
	s_waitcnt lgkmcnt(0)
	v_add_f32_e32 v34, v34, v35
	v_xor_b32_e32 v35, 32, v245
	v_cmp_lt_i32_e32 vcc, v35, v36
	s_nop 1
	v_cndmask_b32_e32 v35, v245, v35, vcc
	v_lshlrev_b32_e32 v35, 2, v35
	v_mov_b32_e32 v35, v34
	s_nop 1
	v_permlane32_swap_b32_e32 v35, v34
	s_and_saveexec_b64 vcc, s[4:5]
	s_cbranch_execz .LBB0_625
	v_readlane_b32 s26, v255, 5
	s_waitcnt lgkmcnt(0)
	v_add_f32_e32 v36, v34, v35
	v_lshlrev_b64 v[34:35], 6, v[224:225]
	v_readlane_b32 s27, v255, 6
	s_lshl_b32 s46, s43, 2
	s_nop 0
	v_lshl_add_u64 v[34:35], s[26:27], 0, v[34:35]
	v_lshl_add_u64 v[34:35], s[82:83], 2, v[34:35]
	v_lshl_add_u64 v[34:35], v[34:35], 0, s[46:47]
	global_store_dword v[34:35], v36, off

; DI unsigned cvtpk(float lo, float hi) { f32x2_t v = {lo, hi}; bf16x2_t b = __builtin_convertvector(v, bf16x2_t); return __builtin_bit_cast(unsigned, b); }
;     DI void operator()(const f32x4 (&acc)[2][2][4][2], const Unit& u, int wr, int wc, int fr, int fq) const {
;     ...
;                 const int row = row0 + ai * HALF + m * 16; float ss = 0.f;
; #pragma unroll
;                 for (int bj = 0; bj < 2; ++bj) {
;                     const size_t off = (size_t)row * DM + col0 + bj * HALF;
;                     const f32x4 b0 = *(const f32x4*)(base + off), b1 = *(const f32x4*)(base + off + 4);
;                     const f32x4 x0 = b0 + alpha * acc[ai][bj][m][0], x1 = b1 + alpha * acc[ai][bj][m][1];
;                     if (out) { *(f32x4*)(out + off) = x0; *(f32x4*)(out + off + 4) = x1; }
;                     if (xb) { u32x4 w; w.x = cvtpk(x0[0], x0[1]); w.y = cvtpk(x0[2], x0[3]); w.z = cvtpk(x1[0], x1[1]); w.w = cvtpk(x1[2], x1[3]); *(u32x4*)(xb + off) = w; }
;                     ss += (x0[0] * x0[0] + x0[1] * x0[1]) + (x0[2] * x0[2] + x0[3] * x0[3]) + (x1[0] * x1[0] + x1[1] * x1[1]) + (x1[2] * x1[2] + x1[3] * x1[3]);
;                 }
;                 if (rss) { ss += __shfl_xor(ss, 16); ss += __shfl_xor(ss, 32); if (fq == 0) rss[(size_t)row * 16 + u.pn * 4 + wc] = ss; }
.LBB0_634:
	s_and_b64 vcc, exec, s[12:13]
	s_cbranch_vccnz .LBB0_638
	v_mul_f32_e32 v31, v31, v31
	v_mul_f32_e32 v21, v21, v21
	v_mul_f32_e32 v19, v19, v19
	v_fmac_f32_e32 v31, v30, v30
	v_mul_f32_e32 v30, v33, v33
	v_fmac_f32_e32 v21, v20, v20
	v_fmac_f32_e32 v19, v18, v18
	v_mul_f32_e32 v18, v23, v23
	v_mul_f32_e32 v20, v25, v25
	v_fmac_f32_e32 v30, v32, v32
	v_mul_f32_e32 v27, v27, v27
	v_fmac_f32_e32 v18, v22, v22
	v_fmac_f32_e32 v20, v24, v24
	v_add_f32_e32 v30, v31, v30
	v_fmac_f32_e32 v27, v26, v26
	v_add_f32_e32 v18, v18, v20
	v_and_b32_e32 v20, 64, v245
	v_add_f32_e32 v26, v27, v30
	v_mul_f32_e32 v27, v29, v29
	v_add_f32_e32 v18, v19, v18
	v_xor_b32_e32 v19, 16, v245
	v_add_u32_e32 v20, 64, v20
	v_fmac_f32_e32 v27, v28, v28
	v_cmp_lt_i32_e32 vcc, v19, v20
	v_add_f32_e32 v26, v27, v26
	v_add_f32_e32 v18, v21, v18
	v_cndmask_b32_e32 v19, v245, v19, vcc
	v_add_f32_e32 v18, v26, v18
	v_lshlrev_b32_e32 v19, 2, v19
	v_mov_b32_e32 v19, v18
	s_nop 1
	v_permlane16_swap_b32_e32 v19, v18
	s_waitcnt lgkmcnt(0)
	v_add_f32_e32 v18, v18, v19
	v_xor_b32_e32 v19, 32, v245
	v_cmp_lt_i32_e32 vcc, v19, v20
	s_nop 1
	v_cndmask_b32_e32 v19, v245, v19, vcc
	v_lshlrev_b32_e32 v19, 2, v19
	v_mov_b32_e32 v19, v18
	s_nop 1
	v_permlane32_swap_b32_e32 v19, v18
	s_and_saveexec_b64 vcc, s[4:5]
	s_cbranch_execz .LBB0_637
	v_readlane_b32 s26, v255, 5
	s_waitcnt lgkmcnt(0)
	v_add_f32_e32 v20, v18, v19
	v_lshlrev_b64 v[18:19], 6, v[222:223]
	v_readlane_b32 s27, v255, 6
	s_lshl_b32 s46, s43, 2
	s_nop 0
	v_lshl_add_u64 v[18:19], s[26:27], 0, v[18:19]
	v_lshl_add_u64 v[18:19], s[82:83], 2, v[18:19]
	v_lshl_add_u64 v[18:19], v[18:19], 0, s[46:47]
	global_store_dword v[18:19], v20, off

; DI unsigned cvtpk(float lo, float hi) { f32x2_t v = {lo, hi}; bf16x2_t b = __builtin_convertvector(v, bf16x2_t); return __builtin_bit_cast(unsigned, b); }
;     DI void operator()(const f32x4 (&acc)[2][2][4][2], const Unit& u, int wr, int wc, int fr, int fq) const {
;     ...
;                 const int row = row0 + ai * HALF + m * 16; float ss = 0.f;
; #pragma unroll
;                 for (int bj = 0; bj < 2; ++bj) {
;                     const size_t off = (size_t)row * DM + col0 + bj * HALF;
;                     const f32x4 b0 = *(const f32x4*)(base + off), b1 = *(const f32x4*)(base + off + 4);
;                     const f32x4 x0 = b0 + alpha * acc[ai][bj][m][0], x1 = b1 + alpha * acc[ai][bj][m][1];
;                     if (out) { *(f32x4*)(out + off) = x0; *(f32x4*)(out + off + 4) = x1; }
;                     if (xb) { u32x4 w; w.x = cvtpk(x0[0], x0[1]); w.y = cvtpk(x0[2], x0[3]); w.z = cvtpk(x1[0], x1[1]); w.w = cvtpk(x1[2], x1[3]); *(u32x4*)(xb + off) = w; }
;                     ss += (x0[0] * x0[0] + x0[1] * x0[1]) + (x0[2] * x0[2] + x0[3] * x0[3]) + (x1[0] * x1[0] + x1[1] * x1[1]) + (x1[2] * x1[2] + x1[3] * x1[3]);
;                 }
;                 if (rss) { ss += __shfl_xor(ss, 16); ss += __shfl_xor(ss, 32); if (fq == 0) rss[(size_t)row * 16 + u.pn * 4 + wc] = ss; }
.LBB0_646:
	s_and_b64 vcc, exec, s[12:13]
	s_cbranch_vccnz .LBB0_650
	v_mul_f32_e32 v15, v15, v15
	v_mul_f32_e32 v5, v5, v5
	v_mul_f32_e32 v3, v3, v3
	v_fmac_f32_e32 v15, v14, v14
	v_mul_f32_e32 v14, v17, v17
	v_fmac_f32_e32 v5, v4, v4
	v_fmac_f32_e32 v3, v2, v2
	v_mul_f32_e32 v2, v7, v7
	v_mul_f32_e32 v4, v9, v9
	v_fmac_f32_e32 v14, v16, v16
	v_mul_f32_e32 v11, v11, v11
	v_fmac_f32_e32 v2, v6, v6
	v_fmac_f32_e32 v4, v8, v8
	v_add_f32_e32 v14, v15, v14
	v_fmac_f32_e32 v11, v10, v10
	v_add_f32_e32 v2, v2, v4
	v_and_b32_e32 v4, 64, v245
	v_add_f32_e32 v10, v11, v14
	v_mul_f32_e32 v11, v13, v13
	v_add_f32_e32 v2, v3, v2
	v_xor_b32_e32 v3, 16, v245
	v_add_u32_e32 v4, 64, v4
	v_fmac_f32_e32 v11, v12, v12
	v_cmp_lt_i32_e32 vcc, v3, v4
	v_add_f32_e32 v10, v11, v10
	v_add_f32_e32 v2, v5, v2
	v_cndmask_b32_e32 v3, v245, v3, vcc
	v_add_f32_e32 v2, v10, v2
	v_lshlrev_b32_e32 v3, 2, v3
	v_mov_b32_e32 v3, v2
	s_nop 1
	v_permlane16_swap_b32_e32 v3, v2
	s_waitcnt lgkmcnt(0)
	v_add_f32_e32 v2, v2, v3
	v_xor_b32_e32 v3, 32, v245
	v_cmp_lt_i32_e32 vcc, v3, v4
	s_nop 1
	v_cndmask_b32_e32 v3, v245, v3, vcc
	v_lshlrev_b32_e32 v3, 2, v3
	v_mov_b32_e32 v3, v2
	s_nop 1
	v_permlane32_swap_b32_e32 v3, v2
	s_and_saveexec_b64 s[8:9], s[4:5]
	s_cbranch_execz .LBB0_649
	v_readlane_b32 s10, v255, 5
	s_waitcnt lgkmcnt(0)
	v_add_f32_e32 v4, v2, v3
	v_lshlrev_b64 v[2:3], 6, v[218:219]
	v_readlane_b32 s11, v255, 6
	s_lshl_b32 s46, s43, 2
	s_nop 0
	v_lshl_add_u64 v[2:3], s[10:11], 0, v[2:3]
	v_lshl_add_u64 v[2:3], s[82:83], 2, v[2:3]
	v_lshl_add_u64 v[2:3], v[2:3], 0, s[46:47]
	global_store_dword v[2:3], v4, off
